# phase 1 big tiles: per-segment s_setprio flips removed, one static priority raise for the second co-resident block (blockIdx >= 256)
# speedup vs baseline: 1.0015x; 1.0015x over previous
.LBB0_116:
	s_or_b64 exec, exec, s[0:1]
	s_add_u32 s0, s94, 0x15000000
	s_addc_u32 s1, s95, 0
	s_add_u32 s28, s94, 0x6c00000
	v_writelane_b32 v242, s0, 50
	s_addc_u32 s29, s95, 0
	v_mov_b32_e32 v0, v199
	v_writelane_b32 v242, s1, 51
	s_add_u32 s0, s94, 0xd000000
	s_addc_u32 s1, s95, 0
	v_writelane_b32 v242, s0, 52
	s_barrier
	s_nop 0
	v_writelane_b32 v242, s1, 53
	s_nop 0
	v_readlane_b32 s0, v242, 45
	v_readlane_b32 s1, v242, 46
	s_cmpk_gt_i32 s0, 0x29ff
	v_writelane_b32 v242, s58, 54
	s_nop 1
	v_writelane_b32 v242, s59, 55
	s_cbranch_scc1 .LBB0_246
	s_mov_b32 s91, 0
	s_cmp_lg_u32 s96, 0x200
	s_cbranch_scc1 .Lbig_skip
	v_lshrrev_b32_e32 v236, 3, v199
	v_lshrrev_b32_e32 v237, 4, v199
	v_xor_b32_e32 v237, v237, v199
	v_and_b32_e32 v237, 7, v237
	v_lshlrev_b32_e32 v237, 4, v237
	v_lshl_add_u32 v192, v236, 12, v237
	v_add_u32_e32 v193, 0x20000, v192
	v_add_u32_e32 v194, 0x40000, v192
	v_add_u32_e32 v195, 0x60000, v192
	v_and_b32_e32 v236, 15, v199
	v_bfe_u32 v237, v199, 4, 2
	v_lshrrev_b32_e32 v238, 1, v236
	v_lshlrev_b32_e32 v202, 3, v237
	v_xor_b32_e32 v237, v237, v238
	v_lshlrev_b32_e32 v237, 4, v237
	v_xor_b32_e32 v238, 64, v237
	v_lshrrev_b32_e32 v201, 7, v199
	v_lshl_add_u32 v201, v201, 7, v236
	v_lshlrev_b32_e32 v196, 7, v201
	v_bfe_u32 v198, v199, 6, 1
	v_lshl_add_u32 v202, v198, 7, v202
	v_lshl_add_u32 v198, v198, 6, v236
	v_lshlrev_b32_e32 v198, 7, v198
	v_add_u32_e32 v198, 0x8000, v198
	v_add_u32_e32 v197, v196, v238
	v_add_u32_e32 v200, v198, v238
	v_add_u32_e32 v196, v196, v237
	v_add_u32_e32 v198, v198, v237
	v_lshrrev_b32_e32 v236, 6, v199
	v_lshlrev_b32_e32 v236, 10, v236
	s_nop 0
	v_readfirstlane_b32 s32, v236
	v_lshrrev_b32_e32 v240, 6, v199
	v_mul_u32_u24_e32 v240, 0x900, v240
	v_add_u32_e32 v240, 0xc000, v240
	v_and_b32_e32 v241, 15, v199
	v_mul_u32_u24_e32 v241, 0x90, v241
	v_bfe_u32 v238, v199, 4, 2
	v_lshl_add_u32 v241, v238, 3, v241
	v_add_u32_e32 v236, v240, v241
	v_and_b32_e32 v241, 63, v199
	v_lshrrev_b32_e32 v238, 3, v241
	v_mul_u32_u24_e32 v238, 0x90, v238
	v_and_b32_e32 v241, 7, v241
	v_lshl_add_u32 v238, v241, 4, v238
	v_add_u32_e32 v237, v240, v238
	v_readlane_b32 s90, v242, 45
	s_cmp_lt_u32 s90, 0x100
	s_cbranch_scc1 .Lbig_prio
	s_setprio 1
.Lbig_prio:
	s_and_b32 s51, s90, 63
	s_lshl_b32 s51, s51, 20
	s_add_u32 s36, s94, s51
	s_addc_u32 s37, s95, 0
	s_add_u32 s36, s36, 0x15000000
	s_addc_u32 s37, s37, 0
	s_lshr_b32 s51, s90, 6
	s_lshl_b32 s51, s51, 19
	s_add_u32 s44, s94, s51
	s_addc_u32 s45, s95, 0
	s_add_u32 s44, s44, 0x19000000
	s_addc_u32 s45, s45, 0
	s_add_u32 s40, s36, 0x80000
	s_addc_u32 s41, s37, 0
	s_and_b32 s21, s90, 31
	s_mov_b32 s20, s21
	s_lshl_b32 s51, s21, 7
	s_add_u32 s36, s36, s51
	s_addc_u32 s37, s37, 0
	s_add_u32 s40, s40, s51
	s_addc_u32 s41, s41, 0
	s_add_u32 s44, s44, s51
	s_addc_u32 s45, s45, 0
	s_barrier
	s_add_u32 m0, s32, 0x0
	s_nop 0
	global_load_lds_dwordx4 v192, s[36:37]
	s_add_u32 m0, s32, 0x1000
	s_nop 0
	global_load_lds_dwordx4 v193, s[36:37]
	s_add_u32 m0, s32, 0x2000
	s_nop 0
	global_load_lds_dwordx4 v194, s[36:37]
	s_add_u32 m0, s32, 0x3000
	s_nop 0
	global_load_lds_dwordx4 v195, s[36:37]
	s_add_u32 m0, s32, 0x4000
	s_nop 0
	global_load_lds_dwordx4 v192, s[40:41]
	s_add_u32 m0, s32, 0x5000
	s_nop 0
	global_load_lds_dwordx4 v193, s[40:41]
	s_add_u32 m0, s32, 0x6000
	s_nop 0
	global_load_lds_dwordx4 v194, s[40:41]
	s_add_u32 m0, s32, 0x7000
	s_nop 0
	global_load_lds_dwordx4 v195, s[40:41]
	s_add_u32 m0, s32, 0x8000
	s_nop 0
	global_load_lds_dwordx4 v192, s[44:45]
	s_add_u32 m0, s32, 0x9000
	s_nop 0
	global_load_lds_dwordx4 v193, s[44:45]
	s_add_u32 m0, s32, 0xa000
	s_nop 0
	global_load_lds_dwordx4 v194, s[44:45]
	s_add_u32 m0, s32, 0xb000
	s_nop 0
	global_load_lds_dwordx4 v195, s[44:45]
	s_add_u32 s36, s36, 0x80
	s_addc_u32 s37, s37, 0
	s_add_u32 s40, s40, 0x80
	s_addc_u32 s41, s41, 0
	s_add_u32 s44, s44, 0x80
	s_addc_u32 s45, s45, 0
	s_add_i32 s20, s20, 1
	s_cmp_eq_u32 s20, 32
	s_cbranch_scc1 .Lbig_wrap0

.Lbig_k_in:
	s_barrier
	ds_read_b128 v[160:163], v198 offset:0
	ds_read_b128 v[164:167], v198 offset:2048
	ds_read_b128 v[168:171], v198 offset:4096
	ds_read_b128 v[172:175], v198 offset:6144
	ds_read_b128 v[128:131], v196 offset:0
	ds_read_b128 v[132:135], v196 offset:2048
	ds_read_b128 v[136:139], v196 offset:4096
	ds_read_b128 v[140:143], v196 offset:6144
	ds_read_b128 v[144:147], v196 offset:8192
	ds_read_b128 v[148:151], v196 offset:10240
	ds_read_b128 v[152:155], v196 offset:12288
	ds_read_b128 v[156:159], v196 offset:14336
	ds_read_b128 v[176:179], v200 offset:0
	ds_read_b128 v[180:183], v200 offset:2048
	ds_read_b128 v[184:187], v200 offset:4096
	ds_read_b128 v[188:191], v200 offset:6144
	ds_read_b128 v[204:207], v197 offset:0
	ds_read_b128 v[208:211], v197 offset:2048
	ds_read_b128 v[212:215], v197 offset:4096
	ds_read_b128 v[216:219], v197 offset:6144
	ds_read_b128 v[220:223], v197 offset:8192
	ds_read_b128 v[224:227], v197 offset:10240
	ds_read_b128 v[228:231], v197 offset:12288
	ds_read_b128 v[232:235], v197 offset:14336
	s_waitcnt lgkmcnt(12)
	v_mfma_f32_16x16x32_bf16 v[0:3], v[160:163], v[128:131], v[0:3]
	v_mfma_f32_16x16x32_bf16 v[4:7], v[164:167], v[128:131], v[4:7]
	v_mfma_f32_16x16x32_bf16 v[8:11], v[168:171], v[128:131], v[8:11]
	v_mfma_f32_16x16x32_bf16 v[12:15], v[172:175], v[128:131], v[12:15]
	v_mfma_f32_16x16x32_bf16 v[16:19], v[160:163], v[132:135], v[16:19]
	v_mfma_f32_16x16x32_bf16 v[20:23], v[164:167], v[132:135], v[20:23]
	v_mfma_f32_16x16x32_bf16 v[24:27], v[168:171], v[132:135], v[24:27]
	v_mfma_f32_16x16x32_bf16 v[28:31], v[172:175], v[132:135], v[28:31]
	v_mfma_f32_16x16x32_bf16 v[32:35], v[160:163], v[136:139], v[32:35]
	v_mfma_f32_16x16x32_bf16 v[36:39], v[164:167], v[136:139], v[36:39]
	v_mfma_f32_16x16x32_bf16 v[40:43], v[168:171], v[136:139], v[40:43]
	v_mfma_f32_16x16x32_bf16 v[44:47], v[172:175], v[136:139], v[44:47]
	v_mfma_f32_16x16x32_bf16 v[48:51], v[160:163], v[140:143], v[48:51]
	v_mfma_f32_16x16x32_bf16 v[52:55], v[164:167], v[140:143], v[52:55]
	v_mfma_f32_16x16x32_bf16 v[56:59], v[168:171], v[140:143], v[56:59]
	v_mfma_f32_16x16x32_bf16 v[60:63], v[172:175], v[140:143], v[60:63]
	v_mfma_f32_16x16x32_bf16 v[64:67], v[160:163], v[144:147], v[64:67]
	v_mfma_f32_16x16x32_bf16 v[68:71], v[164:167], v[144:147], v[68:71]
	v_mfma_f32_16x16x32_bf16 v[72:75], v[168:171], v[144:147], v[72:75]
	v_mfma_f32_16x16x32_bf16 v[76:79], v[172:175], v[144:147], v[76:79]
	v_mfma_f32_16x16x32_bf16 v[80:83], v[160:163], v[148:151], v[80:83]
	v_mfma_f32_16x16x32_bf16 v[84:87], v[164:167], v[148:151], v[84:87]
	v_mfma_f32_16x16x32_bf16 v[88:91], v[168:171], v[148:151], v[88:91]
	v_mfma_f32_16x16x32_bf16 v[92:95], v[172:175], v[148:151], v[92:95]
	v_mfma_f32_16x16x32_bf16 v[96:99], v[160:163], v[152:155], v[96:99]
	v_mfma_f32_16x16x32_bf16 v[100:103], v[164:167], v[152:155], v[100:103]
	v_mfma_f32_16x16x32_bf16 v[104:107], v[168:171], v[152:155], v[104:107]
	v_mfma_f32_16x16x32_bf16 v[108:111], v[172:175], v[152:155], v[108:111]
	v_mfma_f32_16x16x32_bf16 v[112:115], v[160:163], v[156:159], v[112:115]
	v_mfma_f32_16x16x32_bf16 v[116:119], v[164:167], v[156:159], v[116:119]
	v_mfma_f32_16x16x32_bf16 v[120:123], v[168:171], v[156:159], v[120:123]
	v_mfma_f32_16x16x32_bf16 v[124:127], v[172:175], v[156:159], v[124:127]
	s_waitcnt lgkmcnt(0)
	s_barrier
	s_add_u32 m0, s32, 0x0
	s_nop 0
	global_load_lds_dwordx4 v192, s[36:37]
	s_add_u32 m0, s32, 0x1000
	s_nop 0
	global_load_lds_dwordx4 v193, s[36:37]
	s_add_u32 m0, s32, 0x2000
	s_nop 0
	global_load_lds_dwordx4 v194, s[36:37]
	s_add_u32 m0, s32, 0x3000
	s_nop 0
	global_load_lds_dwordx4 v195, s[36:37]
	s_add_u32 m0, s32, 0x4000
	s_nop 0
	global_load_lds_dwordx4 v192, s[40:41]
	s_add_u32 m0, s32, 0x5000
	s_nop 0
	global_load_lds_dwordx4 v193, s[40:41]
	s_add_u32 m0, s32, 0x6000
	s_nop 0
	global_load_lds_dwordx4 v194, s[40:41]
	s_add_u32 m0, s32, 0x7000
	s_nop 0
	global_load_lds_dwordx4 v195, s[40:41]
	s_add_u32 m0, s32, 0x8000
	s_nop 0
	global_load_lds_dwordx4 v192, s[44:45]
	s_add_u32 m0, s32, 0x9000
	s_nop 0
	global_load_lds_dwordx4 v193, s[44:45]
	s_add_u32 m0, s32, 0xa000
	s_nop 0
	global_load_lds_dwordx4 v194, s[44:45]
	s_add_u32 m0, s32, 0xb000
	s_nop 0
	global_load_lds_dwordx4 v195, s[44:45]
	s_add_u32 s36, s36, 0x80
	s_addc_u32 s37, s37, 0
	s_add_u32 s40, s40, 0x80
	s_addc_u32 s41, s41, 0
	s_add_u32 s44, s44, 0x80
	s_addc_u32 s45, s45, 0
	s_add_i32 s20, s20, 1
	s_cmp_eq_u32 s20, 32
	s_cbranch_scc1 .Lbig_wrap1
.Lbig_wrapret1:
	v_mfma_f32_16x16x32_bf16 v[0:3], v[176:179], v[204:207], v[0:3]
	v_mfma_f32_16x16x32_bf16 v[4:7], v[180:183], v[204:207], v[4:7]
	v_mfma_f32_16x16x32_bf16 v[8:11], v[184:187], v[204:207], v[8:11]
	v_mfma_f32_16x16x32_bf16 v[12:15], v[188:191], v[204:207], v[12:15]
	v_mfma_f32_16x16x32_bf16 v[16:19], v[176:179], v[208:211], v[16:19]
	v_mfma_f32_16x16x32_bf16 v[20:23], v[180:183], v[208:211], v[20:23]
	v_mfma_f32_16x16x32_bf16 v[24:27], v[184:187], v[208:211], v[24:27]
	v_mfma_f32_16x16x32_bf16 v[28:31], v[188:191], v[208:211], v[28:31]
	v_mfma_f32_16x16x32_bf16 v[32:35], v[176:179], v[212:215], v[32:35]
	v_mfma_f32_16x16x32_bf16 v[36:39], v[180:183], v[212:215], v[36:39]
	v_mfma_f32_16x16x32_bf16 v[40:43], v[184:187], v[212:215], v[40:43]
	v_mfma_f32_16x16x32_bf16 v[44:47], v[188:191], v[212:215], v[44:47]
	v_mfma_f32_16x16x32_bf16 v[48:51], v[176:179], v[216:219], v[48:51]
	v_mfma_f32_16x16x32_bf16 v[52:55], v[180:183], v[216:219], v[52:55]
	v_mfma_f32_16x16x32_bf16 v[56:59], v[184:187], v[216:219], v[56:59]
	v_mfma_f32_16x16x32_bf16 v[60:63], v[188:191], v[216:219], v[60:63]
	v_mfma_f32_16x16x32_bf16 v[64:67], v[176:179], v[220:223], v[64:67]
	v_mfma_f32_16x16x32_bf16 v[68:71], v[180:183], v[220:223], v[68:71]
	v_mfma_f32_16x16x32_bf16 v[72:75], v[184:187], v[220:223], v[72:75]
	v_mfma_f32_16x16x32_bf16 v[76:79], v[188:191], v[220:223], v[76:79]
	v_mfma_f32_16x16x32_bf16 v[80:83], v[176:179], v[224:227], v[80:83]
	v_mfma_f32_16x16x32_bf16 v[84:87], v[180:183], v[224:227], v[84:87]
	v_mfma_f32_16x16x32_bf16 v[88:91], v[184:187], v[224:227], v[88:91]
	v_mfma_f32_16x16x32_bf16 v[92:95], v[188:191], v[224:227], v[92:95]
	v_mfma_f32_16x16x32_bf16 v[96:99], v[176:179], v[228:231], v[96:99]
	v_mfma_f32_16x16x32_bf16 v[100:103], v[180:183], v[228:231], v[100:103]
	v_mfma_f32_16x16x32_bf16 v[104:107], v[184:187], v[228:231], v[104:107]
	v_mfma_f32_16x16x32_bf16 v[108:111], v[188:191], v[228:231], v[108:111]
	v_mfma_f32_16x16x32_bf16 v[112:115], v[176:179], v[232:235], v[112:115]
	v_mfma_f32_16x16x32_bf16 v[116:119], v[180:183], v[232:235], v[116:119]
	v_mfma_f32_16x16x32_bf16 v[120:123], v[184:187], v[232:235], v[120:123]
	v_mfma_f32_16x16x32_bf16 v[124:127], v[188:191], v[232:235], v[124:127]
	s_add_i32 s50, s50, 1
	s_cmp_lt_u32 s50, 31
	s_cbranch_scc1 .Lbig_k
	s_waitcnt vmcnt(0)
	s_barrier
	ds_read_b128 v[160:163], v198 offset:0
	ds_read_b128 v[164:167], v198 offset:2048
	ds_read_b128 v[168:171], v198 offset:4096
	ds_read_b128 v[172:175], v198 offset:6144
	ds_read_b128 v[128:131], v196 offset:0
	ds_read_b128 v[132:135], v196 offset:2048
	ds_read_b128 v[136:139], v196 offset:4096
	ds_read_b128 v[140:143], v196 offset:6144
	ds_read_b128 v[144:147], v196 offset:8192
	ds_read_b128 v[148:151], v196 offset:10240
	ds_read_b128 v[152:155], v196 offset:12288
	ds_read_b128 v[156:159], v196 offset:14336
	ds_read_b128 v[176:179], v200 offset:0
	ds_read_b128 v[180:183], v200 offset:2048
	ds_read_b128 v[184:187], v200 offset:4096
	ds_read_b128 v[188:191], v200 offset:6144
	ds_read_b128 v[204:207], v197 offset:0
	ds_read_b128 v[208:211], v197 offset:2048
	ds_read_b128 v[212:215], v197 offset:4096
	ds_read_b128 v[216:219], v197 offset:6144
	ds_read_b128 v[220:223], v197 offset:8192
	ds_read_b128 v[224:227], v197 offset:10240
	ds_read_b128 v[228:231], v197 offset:12288
	ds_read_b128 v[232:235], v197 offset:14336
	s_waitcnt lgkmcnt(12)
	v_mfma_f32_16x16x32_bf16 v[0:3], v[160:163], v[128:131], v[0:3]
	v_mfma_f32_16x16x32_bf16 v[4:7], v[164:167], v[128:131], v[4:7]
	v_mfma_f32_16x16x32_bf16 v[8:11], v[168:171], v[128:131], v[8:11]
	v_mfma_f32_16x16x32_bf16 v[12:15], v[172:175], v[128:131], v[12:15]
	v_mfma_f32_16x16x32_bf16 v[16:19], v[160:163], v[132:135], v[16:19]
	v_mfma_f32_16x16x32_bf16 v[20:23], v[164:167], v[132:135], v[20:23]
	v_mfma_f32_16x16x32_bf16 v[24:27], v[168:171], v[132:135], v[24:27]
	v_mfma_f32_16x16x32_bf16 v[28:31], v[172:175], v[132:135], v[28:31]
	v_mfma_f32_16x16x32_bf16 v[32:35], v[160:163], v[136:139], v[32:35]
	v_mfma_f32_16x16x32_bf16 v[36:39], v[164:167], v[136:139], v[36:39]
	v_mfma_f32_16x16x32_bf16 v[40:43], v[168:171], v[136:139], v[40:43]
	v_mfma_f32_16x16x32_bf16 v[44:47], v[172:175], v[136:139], v[44:47]
	v_mfma_f32_16x16x32_bf16 v[48:51], v[160:163], v[140:143], v[48:51]
	v_mfma_f32_16x16x32_bf16 v[52:55], v[164:167], v[140:143], v[52:55]
	v_mfma_f32_16x16x32_bf16 v[56:59], v[168:171], v[140:143], v[56:59]
	v_mfma_f32_16x16x32_bf16 v[60:63], v[172:175], v[140:143], v[60:63]
	v_mfma_f32_16x16x32_bf16 v[64:67], v[160:163], v[144:147], v[64:67]
	v_mfma_f32_16x16x32_bf16 v[68:71], v[164:167], v[144:147], v[68:71]
	v_mfma_f32_16x16x32_bf16 v[72:75], v[168:171], v[144:147], v[72:75]
	v_mfma_f32_16x16x32_bf16 v[76:79], v[172:175], v[144:147], v[76:79]
	v_mfma_f32_16x16x32_bf16 v[80:83], v[160:163], v[148:151], v[80:83]
	v_mfma_f32_16x16x32_bf16 v[84:87], v[164:167], v[148:151], v[84:87]
	v_mfma_f32_16x16x32_bf16 v[88:91], v[168:171], v[148:151], v[88:91]
	v_mfma_f32_16x16x32_bf16 v[92:95], v[172:175], v[148:151], v[92:95]
	v_mfma_f32_16x16x32_bf16 v[96:99], v[160:163], v[152:155], v[96:99]
	v_mfma_f32_16x16x32_bf16 v[100:103], v[164:167], v[152:155], v[100:103]
	v_mfma_f32_16x16x32_bf16 v[104:107], v[168:171], v[152:155], v[104:107]
	v_mfma_f32_16x16x32_bf16 v[108:111], v[172:175], v[152:155], v[108:111]
	v_mfma_f32_16x16x32_bf16 v[112:115], v[160:163], v[156:159], v[112:115]
	v_mfma_f32_16x16x32_bf16 v[116:119], v[164:167], v[156:159], v[116:119]
	v_mfma_f32_16x16x32_bf16 v[120:123], v[168:171], v[156:159], v[120:123]
	v_mfma_f32_16x16x32_bf16 v[124:127], v[172:175], v[156:159], v[124:127]
	s_waitcnt lgkmcnt(0)
	s_cmp_ge_u32 s91, 0x1400
	s_cbranch_scc1 .Lbig_nonext
	s_barrier
	s_mov_b64 s[36:37], s[46:47]
	s_mov_b64 s[44:45], s[48:49]
	s_add_u32 s40, s36, 0x80000
	s_addc_u32 s41, s37, 0
	s_mov_b32 s20, s21
	s_add_u32 m0, s32, 0x0
	s_nop 0
	global_load_lds_dwordx4 v192, s[36:37]
	s_add_u32 m0, s32, 0x1000
	s_nop 0
	global_load_lds_dwordx4 v193, s[36:37]
	s_add_u32 m0, s32, 0x2000
	s_nop 0
	global_load_lds_dwordx4 v194, s[36:37]
	s_add_u32 m0, s32, 0x3000
	s_nop 0
	global_load_lds_dwordx4 v195, s[36:37]
	s_add_u32 m0, s32, 0x4000
	s_nop 0
	global_load_lds_dwordx4 v192, s[40:41]
	s_add_u32 m0, s32, 0x5000
	s_nop 0
	global_load_lds_dwordx4 v193, s[40:41]
	s_add_u32 m0, s32, 0x6000
	s_nop 0
	global_load_lds_dwordx4 v194, s[40:41]
	s_add_u32 m0, s32, 0x7000
	s_nop 0
	global_load_lds_dwordx4 v195, s[40:41]
	s_add_u32 m0, s32, 0x8000
	s_nop 0
	global_load_lds_dwordx4 v192, s[44:45]
	s_add_u32 m0, s32, 0x9000
	s_nop 0
	global_load_lds_dwordx4 v193, s[44:45]
	s_add_u32 m0, s32, 0xa000
	s_nop 0
	global_load_lds_dwordx4 v194, s[44:45]
	s_add_u32 m0, s32, 0xb000
	s_nop 0
	global_load_lds_dwordx4 v195, s[44:45]
	s_add_u32 s36, s36, 0x80
	s_addc_u32 s37, s37, 0
	s_add_u32 s40, s40, 0x80
	s_addc_u32 s41, s41, 0
	s_add_u32 s44, s44, 0x80
	s_addc_u32 s45, s45, 0
	s_add_i32 s20, s20, 1
	s_cmp_eq_u32 s20, 32
	s_cbranch_scc1 .Lbig_wrap2
.Lbig_wrapret2:
.Lbig_nonext:
	v_mfma_f32_16x16x32_bf16 v[0:3], v[176:179], v[204:207], v[0:3]
	v_mfma_f32_16x16x32_bf16 v[4:7], v[180:183], v[204:207], v[4:7]
	v_mfma_f32_16x16x32_bf16 v[8:11], v[184:187], v[204:207], v[8:11]
	v_mfma_f32_16x16x32_bf16 v[12:15], v[188:191], v[204:207], v[12:15]
	v_mfma_f32_16x16x32_bf16 v[16:19], v[176:179], v[208:211], v[16:19]
	v_mfma_f32_16x16x32_bf16 v[20:23], v[180:183], v[208:211], v[20:23]
	v_mfma_f32_16x16x32_bf16 v[24:27], v[184:187], v[208:211], v[24:27]
	v_mfma_f32_16x16x32_bf16 v[28:31], v[188:191], v[208:211], v[28:31]
	v_mfma_f32_16x16x32_bf16 v[32:35], v[176:179], v[212:215], v[32:35]
	v_mfma_f32_16x16x32_bf16 v[36:39], v[180:183], v[212:215], v[36:39]
	v_mfma_f32_16x16x32_bf16 v[40:43], v[184:187], v[212:215], v[40:43]
	v_mfma_f32_16x16x32_bf16 v[44:47], v[188:191], v[212:215], v[44:47]
	v_mfma_f32_16x16x32_bf16 v[48:51], v[176:179], v[216:219], v[48:51]
	v_mfma_f32_16x16x32_bf16 v[52:55], v[180:183], v[216:219], v[52:55]
	v_mfma_f32_16x16x32_bf16 v[56:59], v[184:187], v[216:219], v[56:59]
	v_mfma_f32_16x16x32_bf16 v[60:63], v[188:191], v[216:219], v[60:63]
	v_mfma_f32_16x16x32_bf16 v[64:67], v[176:179], v[220:223], v[64:67]
	v_mfma_f32_16x16x32_bf16 v[68:71], v[180:183], v[220:223], v[68:71]
	v_mfma_f32_16x16x32_bf16 v[72:75], v[184:187], v[220:223], v[72:75]
	v_mfma_f32_16x16x32_bf16 v[76:79], v[188:191], v[220:223], v[76:79]
	v_mfma_f32_16x16x32_bf16 v[80:83], v[176:179], v[224:227], v[80:83]
	v_mfma_f32_16x16x32_bf16 v[84:87], v[180:183], v[224:227], v[84:87]
	v_mfma_f32_16x16x32_bf16 v[88:91], v[184:187], v[224:227], v[88:91]
	v_mfma_f32_16x16x32_bf16 v[92:95], v[188:191], v[224:227], v[92:95]
	v_mfma_f32_16x16x32_bf16 v[96:99], v[176:179], v[228:231], v[96:99]
	v_mfma_f32_16x16x32_bf16 v[100:103], v[180:183], v[228:231], v[100:103]
	v_mfma_f32_16x16x32_bf16 v[104:107], v[184:187], v[228:231], v[104:107]
	v_mfma_f32_16x16x32_bf16 v[108:111], v[188:191], v[228:231], v[108:111]
	v_mfma_f32_16x16x32_bf16 v[112:115], v[176:179], v[232:235], v[112:115]
	v_mfma_f32_16x16x32_bf16 v[116:119], v[180:183], v[232:235], v[116:119]
	v_mfma_f32_16x16x32_bf16 v[120:123], v[184:187], v[232:235], v[120:123]
	v_mfma_f32_16x16x32_bf16 v[124:127], v[188:191], v[232:235], v[124:127]
	s_lshr_b32 s51, s90, 6
	s_lshl_b32 s51, s51, 7
	s_and_b32 s17, s90, 63
	s_lshl_b32 s17, s17, 8
	s_mov_b32 s16, 0x1b00
	s_mov_b32 s18, 0
	s_mov_b32 s19, 0
	s_cmp_lt_u32 s51, 0xd80
	s_cbranch_scc1 .Lbig_reg
	s_mov_b32 s16, 0x1900
	s_mov_b32 s18, 0x6c00000
	s_mov_b32 s19, 0xd80
	s_cmp_lt_u32 s51, 0x1a00
	s_cbranch_scc1 .Lbig_reg
	s_mov_b32 s16, 0x2000
	s_mov_b32 s18, 0xd000000
	s_mov_b32 s19, 0x1a00
.Lbig_reg:
	s_sub_u32 s51, s51, s19
	s_lshl_b32 s51, s51, 1
	s_mul_i32 s17, s17, s16
	s_add_u32 s17, s17, s51
	s_add_u32 s17, s17, s18
	s_add_u32 s14, s94, s17
	s_addc_u32 s15, s95, 0
	s_lshl_b32 s16, s16, 4
	v_and_b32_e32 v241, 63, v199
	v_lshrrev_b32_e32 v240, 3, v241
	v_lshrrev_b32_e32 v238, 7, v199
	v_lshl_add_u32 v238, v238, 7, v240
	v_mul_lo_u32 v203, v238, s16
	v_lshrrev_b32_e32 v203, 4, v203
	v_and_b32_e32 v240, 7, v241
	v_lshl_add_u32 v203, v240, 4, v203
	v_bfe_u32 v240, v199, 6, 1
	v_lshl_add_u32 v203, v240, 7, v203
	s_lshr_b32 s17, s16, 1
	v_add_u32_e32 v238, s17, v203
	v_cvt_pk_bf16_f32 v128, v0, v1
	v_cvt_pk_bf16_f32 v129, v2, v3
	ds_write_b64 v236, v[128:129] offset:0
	v_cvt_pk_bf16_f32 v130, v4, v5
	v_cvt_pk_bf16_f32 v131, v6, v7
	ds_write_b64 v236, v[130:131] offset:32
	v_cvt_pk_bf16_f32 v128, v8, v9
	v_cvt_pk_bf16_f32 v129, v10, v11
	ds_write_b64 v236, v[128:129] offset:64
	v_cvt_pk_bf16_f32 v130, v12, v13
	v_cvt_pk_bf16_f32 v131, v14, v15
	ds_write_b64 v236, v[130:131] offset:96
	s_waitcnt lgkmcnt(0)
	ds_read_b128 v[136:139], v237
	ds_read_b128 v[140:143], v237 offset:1152
	s_waitcnt lgkmcnt(0)
	global_store_dwordx4 v203, v[136:139], s[14:15]
	global_store_dwordx4 v238, v[140:143], s[14:15]
	s_add_u32 s14, s14, s16
	s_addc_u32 s15, s15, 0
	v_cvt_pk_bf16_f32 v128, v16, v17
	v_cvt_pk_bf16_f32 v129, v18, v19
	ds_write_b64 v236, v[128:129] offset:0
	v_cvt_pk_bf16_f32 v130, v20, v21
	v_cvt_pk_bf16_f32 v131, v22, v23
	ds_write_b64 v236, v[130:131] offset:32
	v_cvt_pk_bf16_f32 v128, v24, v25
	v_cvt_pk_bf16_f32 v129, v26, v27
	ds_write_b64 v236, v[128:129] offset:64
	v_cvt_pk_bf16_f32 v130, v28, v29
	v_cvt_pk_bf16_f32 v131, v30, v31
	ds_write_b64 v236, v[130:131] offset:96
	s_waitcnt lgkmcnt(0)
	ds_read_b128 v[136:139], v237
	ds_read_b128 v[140:143], v237 offset:1152
	s_waitcnt lgkmcnt(0)
	global_store_dwordx4 v203, v[136:139], s[14:15]
	global_store_dwordx4 v238, v[140:143], s[14:15]
	s_add_u32 s14, s14, s16
	s_addc_u32 s15, s15, 0
	v_cvt_pk_bf16_f32 v128, v32, v33
	v_cvt_pk_bf16_f32 v129, v34, v35
	ds_write_b64 v236, v[128:129] offset:0
	v_cvt_pk_bf16_f32 v130, v36, v37
	v_cvt_pk_bf16_f32 v131, v38, v39
	ds_write_b64 v236, v[130:131] offset:32
	v_cvt_pk_bf16_f32 v128, v40, v41
	v_cvt_pk_bf16_f32 v129, v42, v43
	ds_write_b64 v236, v[128:129] offset:64
	v_cvt_pk_bf16_f32 v130, v44, v45
	v_cvt_pk_bf16_f32 v131, v46, v47
	ds_write_b64 v236, v[130:131] offset:96
	s_waitcnt lgkmcnt(0)
	ds_read_b128 v[136:139], v237
	ds_read_b128 v[140:143], v237 offset:1152
	s_waitcnt lgkmcnt(0)
	global_store_dwordx4 v203, v[136:139], s[14:15]
	global_store_dwordx4 v238, v[140:143], s[14:15]
	s_add_u32 s14, s14, s16
	s_addc_u32 s15, s15, 0
	v_cvt_pk_bf16_f32 v128, v48, v49
	v_cvt_pk_bf16_f32 v129, v50, v51
	ds_write_b64 v236, v[128:129] offset:0
	v_cvt_pk_bf16_f32 v130, v52, v53
	v_cvt_pk_bf16_f32 v131, v54, v55
	ds_write_b64 v236, v[130:131] offset:32
	v_cvt_pk_bf16_f32 v128, v56, v57
	v_cvt_pk_bf16_f32 v129, v58, v59
	ds_write_b64 v236, v[128:129] offset:64
	v_cvt_pk_bf16_f32 v130, v60, v61
	v_cvt_pk_bf16_f32 v131, v62, v63
	ds_write_b64 v236, v[130:131] offset:96
	s_waitcnt lgkmcnt(0)
	ds_read_b128 v[136:139], v237
	ds_read_b128 v[140:143], v237 offset:1152
	s_waitcnt lgkmcnt(0)
	global_store_dwordx4 v203, v[136:139], s[14:15]
	global_store_dwordx4 v238, v[140:143], s[14:15]
	s_add_u32 s14, s14, s16
	s_addc_u32 s15, s15, 0
	v_cvt_pk_bf16_f32 v128, v64, v65
	v_cvt_pk_bf16_f32 v129, v66, v67
	ds_write_b64 v236, v[128:129] offset:0
	v_cvt_pk_bf16_f32 v130, v68, v69
	v_cvt_pk_bf16_f32 v131, v70, v71
	ds_write_b64 v236, v[130:131] offset:32
	v_cvt_pk_bf16_f32 v128, v72, v73
	v_cvt_pk_bf16_f32 v129, v74, v75
	ds_write_b64 v236, v[128:129] offset:64
	v_cvt_pk_bf16_f32 v130, v76, v77
	v_cvt_pk_bf16_f32 v131, v78, v79
	ds_write_b64 v236, v[130:131] offset:96
	s_waitcnt lgkmcnt(0)
	ds_read_b128 v[136:139], v237
	ds_read_b128 v[140:143], v237 offset:1152
	s_waitcnt lgkmcnt(0)
	global_store_dwordx4 v203, v[136:139], s[14:15]
	global_store_dwordx4 v238, v[140:143], s[14:15]
	s_add_u32 s14, s14, s16
	s_addc_u32 s15, s15, 0
	v_cvt_pk_bf16_f32 v128, v80, v81
	v_cvt_pk_bf16_f32 v129, v82, v83
	ds_write_b64 v236, v[128:129] offset:0
	v_cvt_pk_bf16_f32 v130, v84, v85
	v_cvt_pk_bf16_f32 v131, v86, v87
	ds_write_b64 v236, v[130:131] offset:32
	v_cvt_pk_bf16_f32 v128, v88, v89
	v_cvt_pk_bf16_f32 v129, v90, v91
	ds_write_b64 v236, v[128:129] offset:64
	v_cvt_pk_bf16_f32 v130, v92, v93
	v_cvt_pk_bf16_f32 v131, v94, v95
	ds_write_b64 v236, v[130:131] offset:96
	s_waitcnt lgkmcnt(0)
	ds_read_b128 v[136:139], v237
	ds_read_b128 v[140:143], v237 offset:1152
	s_waitcnt lgkmcnt(0)
	global_store_dwordx4 v203, v[136:139], s[14:15]
	global_store_dwordx4 v238, v[140:143], s[14:15]
	s_add_u32 s14, s14, s16
	s_addc_u32 s15, s15, 0
	v_cvt_pk_bf16_f32 v128, v96, v97
	v_cvt_pk_bf16_f32 v129, v98, v99
	ds_write_b64 v236, v[128:129] offset:0
	v_cvt_pk_bf16_f32 v130, v100, v101
	v_cvt_pk_bf16_f32 v131, v102, v103
	ds_write_b64 v236, v[130:131] offset:32
	v_cvt_pk_bf16_f32 v128, v104, v105
	v_cvt_pk_bf16_f32 v129, v106, v107
	ds_write_b64 v236, v[128:129] offset:64
	v_cvt_pk_bf16_f32 v130, v108, v109
	v_cvt_pk_bf16_f32 v131, v110, v111
	ds_write_b64 v236, v[130:131] offset:96
	s_waitcnt lgkmcnt(0)
	ds_read_b128 v[136:139], v237
	ds_read_b128 v[140:143], v237 offset:1152
	s_waitcnt lgkmcnt(0)
	global_store_dwordx4 v203, v[136:139], s[14:15]
	global_store_dwordx4 v238, v[140:143], s[14:15]
	s_add_u32 s14, s14, s16
	s_addc_u32 s15, s15, 0
	v_cvt_pk_bf16_f32 v128, v112, v113
	v_cvt_pk_bf16_f32 v129, v114, v115
	ds_write_b64 v236, v[128:129] offset:0
	v_cvt_pk_bf16_f32 v130, v116, v117
	v_cvt_pk_bf16_f32 v131, v118, v119
	ds_write_b64 v236, v[130:131] offset:32
	v_cvt_pk_bf16_f32 v128, v120, v121
	v_cvt_pk_bf16_f32 v129, v122, v123
	ds_write_b64 v236, v[128:129] offset:64
	v_cvt_pk_bf16_f32 v130, v124, v125
	v_cvt_pk_bf16_f32 v131, v126, v127
	ds_write_b64 v236, v[130:131] offset:96
	s_waitcnt lgkmcnt(0)
	ds_read_b128 v[136:139], v237
	ds_read_b128 v[140:143], v237 offset:1152
	s_waitcnt lgkmcnt(0)
	global_store_dwordx4 v203, v[136:139], s[14:15]
	global_store_dwordx4 v238, v[140:143], s[14:15]
	s_add_u32 s90, s90, 0x200
	s_cmp_lt_u32 s90, 0x1400
	s_cbranch_scc1 .Lbig_tile
	s_waitcnt vmcnt(0)
	s_setprio 0
	s_mov_b32 s91, 1
	s_branch .Lbig_skip
